# gate-up: the row-statistics LDS-DMA of a tile is skipped when the per-row scale cache already holds this row block (9 of 11 tiles)
# baseline (speedup 1.0000x reference)
; #define PG8_STAGE(bufoff, gbase, voff) do { _Pragma("unroll") for (int _i = 0; _i < 2; ++_i) { \
;         const unsigned _m0 = ldsb + (unsigned)((bufoff) + _i * 8192); const char* _gb = (const char*)(gbase); \
;         asm volatile("s_mov_b32 m0, %0\n\ts_nop 0\n\tglobal_load_lds_dwordx4 %1, %2" :: "s"(_m0), "v"((voff)[_i]), "s"(_gb) : "m0", "memory"); } } while (0)
; #define PG8_WAIT_V(n) asm volatile("s_waitcnt vmcnt(" #n ")" ::: "memory")
; #define PG8_WAIT_L(n) asm volatile("s_waitcnt lgkmcnt(" #n ")" ::: "memory")
; #define PG8_BAR __builtin_amdgcn_s_barrier()
;     __device__ bool next(int i, Unit& u) const {
;         const long L = (long)i * G + c; if (L >= nwg) return false;
;         int wgid = (int)L; { const int q = nwg / NXCD, r = nwg % NXCD, xcd = wgid % NXCD, off = wgid / NXCD; wgid = (xcd < r ? xcd * (q + 1) : r * (q + 1) + (xcd - r) * q) + off; }
;         const int nig = WGM * nN, gid = wgid / nig, fm = gid * WGM, gsz = (nM - fm) < WGM ? (nM - fm) : WGM;
;         u.pm = fm + ((wgid % nig) % gsz); u.pn = (wgid % nig) / gsz; return true;
; template <class Epi, bool ALIGN_EPI>
; __device__ __forceinline__ void gemm_phase(LAS unsigned char* lds, const Gemm g, const StaticOrder& S, const Epi& E) {
;     ...
;         const bool has_next = S.next(ui + 1, nxt);
;         const char* nA = has_next ? (const char*)g.A + (size_t)nxt.pm * tstepA + (size_t)nxt.pn * g.a_pn_off * 2 + (size_t)(nxt.pm >> 4) * g.a_adj : cA; const char* nB = has_next ? (const char*)g.Bt + (size_t)nxt.pn * tstepB : cB;
;         for (int t = 0; t < nt; t += 2) {
;             const bool last = (t == nt - 2);
;             const char* a1 = cA + (size_t)(t + 1) * kstep;
;             const char* a2 = last ? nA : cA + (size_t)(t + 2) * kstep; const char* b2 = last ? nB : cB + (size_t)(t + 2) * kstep;
;             const char* a3 = a2 + kstep; const char* b3 = b2 + kstep;
;             PG8_LDB(B0, 0, 0); PG8_LDB(B1, 0, 1); PG8_SCHED; PG8_LDA(At, 0, 0); PG8_STAGE(PG8_SA(1, 1), a1 + hstepA, voffA);
;             PG8_WAIT_V(8); PG8_WAIT_L(0); PG8_BAR; PG8_MMA(0, 0, At, B0); PG8_MMA(0, 1, At, B1); PG8_BAR; PG8_SCHED;
;             PG8_LDA(At, 0, 1); PG8_STAGE(PG8_SB(0, 0), b2, voffB); PG8_STAGE(PG8_SB(0, 1), b2 + hstepB, voffB); PG8_STAGE(PG8_SA(0, 0), a2, voffA);
;             PG8_WAIT_V(8); PG8_WAIT_L(0); PG8_BAR; PG8_MMA(1, 0, At, B0); PG8_MMA(1, 1, At, B1); PG8_BAR; PG8_SCHED;
.LBB0_305:
	s_add_u32 s41, s56, 0x100
	s_addc_u32 s49, s57, 0
	s_add_u32 s92, s58, 0x40080
	s_addc_u32 s93, s59, 0
	s_mov_b32 s50, -2
	s_add_u32 s30, s92, 0xfffc0080
	s_addc_u32 s31, s93, -1
	s_cmp_eq_u32 s50, 12
	s_cselect_b32 s60, s5, s30
	s_cselect_b32 s61, s4, s31
	s_cselect_b32 s58, s37, s41
	s_cselect_b32 s59, s35, s49
	s_add_u32 s56, s60, 0x80
	s_addc_u32 s57, s61, 0
	s_mov_b32 m0, s67
	s_nop 0
	global_load_lds_dwordx4 v0, s[92:93]
	s_nop 0
	s_mov_b32 m0, s65
	s_nop 0
	global_load_lds_dwordx4 v181, s[92:93]
	s_waitcnt vmcnt(8)
	s_waitcnt lgkmcnt(0)
	s_setprio 1
	s_barrier
	v_mfma_f32_16x16x32_bf16 v[142:145], v[74:77], v[162:165], 0
	v_mfma_f32_16x16x32_bf16 v[142:145], v[94:97], v[166:169], v[142:145]
	v_mfma_f32_16x16x32_bf16 v[138:141], v[114:117], v[162:165], 0
	v_mfma_f32_16x16x32_bf16 v[138:141], v[134:137], v[166:169], v[138:141]
	v_mfma_f32_16x16x32_bf16 v[130:133], v[146:149], v[162:165], 0
	v_mfma_f32_16x16x32_bf16 v[130:133], v[150:153], v[166:169], v[130:133]
	v_mfma_f32_16x16x32_bf16 v[126:129], v[154:157], v[162:165], 0
	v_mfma_f32_16x16x32_bf16 v[126:129], v[158:161], v[166:169], v[126:129]
	v_mfma_f32_16x16x32_bf16 v[106:109], v[154:157], v[170:173], 0
	v_mfma_f32_16x16x32_bf16 v[106:109], v[158:161], v[174:177], v[106:109]
	v_mfma_f32_16x16x32_bf16 v[110:113], v[146:149], v[170:173], 0
	v_mfma_f32_16x16x32_bf16 v[110:113], v[150:153], v[174:177], v[110:113]
	v_mfma_f32_16x16x32_bf16 v[118:121], v[114:117], v[170:173], 0
	v_mfma_f32_16x16x32_bf16 v[118:121], v[134:137], v[174:177], v[118:121]
	v_mfma_f32_16x16x32_bf16 v[122:125], v[74:77], v[170:173], 0
	v_mfma_f32_16x16x32_bf16 v[122:125], v[94:97], v[174:177], v[122:125]
	v_mfma_f32_16x16x32_bf16 v[102:105], v[74:77], v[188:191], 0
	v_mfma_f32_16x16x32_bf16 v[102:105], v[94:97], v[202:205], v[102:105]
	v_mfma_f32_16x16x32_bf16 v[98:101], v[114:117], v[188:191], 0
	v_mfma_f32_16x16x32_bf16 v[98:101], v[134:137], v[202:205], v[98:101]
	v_mfma_f32_16x16x32_bf16 v[90:93], v[146:149], v[188:191], 0
	v_mfma_f32_16x16x32_bf16 v[90:93], v[150:153], v[202:205], v[90:93]
	v_mfma_f32_16x16x32_bf16 v[86:89], v[154:157], v[188:191], 0
	v_mfma_f32_16x16x32_bf16 v[86:89], v[158:161], v[202:205], v[86:89]
	v_mfma_f32_16x16x32_bf16 v[66:69], v[154:157], v[206:209], 0
	v_mfma_f32_16x16x32_bf16 v[66:69], v[158:161], v[210:213], v[66:69]
	v_mfma_f32_16x16x32_bf16 v[70:73], v[146:149], v[206:209], 0
	v_mfma_f32_16x16x32_bf16 v[70:73], v[150:153], v[210:213], v[70:73]
	v_mfma_f32_16x16x32_bf16 v[78:81], v[114:117], v[206:209], 0
	v_mfma_f32_16x16x32_bf16 v[78:81], v[134:137], v[210:213], v[78:81]
	v_mfma_f32_16x16x32_bf16 v[82:85], v[74:77], v[206:209], 0
	v_mfma_f32_16x16x32_bf16 v[82:85], v[94:97], v[210:213], v[82:85]
	s_barrier
	s_setprio 0
	s_cmp_eq_u32 s54, s98
	s_cbranch_scc1 .Lstat_skip
	v_mbcnt_lo_u32_b32 v178, -1, 0
	v_mbcnt_hi_u32_b32 v178, -1, v178
	s_lshl_b32 s90, s54, 8
	s_add_i32 s90, s90, s89
	s_lshl_b32 s91, s89, 4
	s_add_i32 s91, s91, 0x23000
	v_add_lshl_u32 v178, v178, s90, 4
	s_mov_b32 m0, s91
	s_nop 0
	global_load_lds_dwordx4 v178, s[24:25]
	global_load_lds_dwordx4 v178, s[24:25] offset:2048
.Lstat_skip:
	ds_read_b128 v[162:165], v186 offset:16384
	ds_read_b128 v[166:169], v186 offset:17408
	ds_read_b128 v[170:173], v186 offset:18432
	ds_read_b128 v[174:177], v186 offset:19456
	ds_read_b128 v[188:191], v186 offset:20480
	ds_read_b128 v[202:205], v186 offset:21504
	ds_read_b128 v[206:209], v186 offset:22528
	ds_read_b128 v[210:213], v186 offset:23552
	s_mov_b32 m0, s29
	s_nop 0
	global_load_lds_dwordx4 v180, s[58:59]
	s_add_u32 s30, s58, 0x40000
	s_mov_b32 m0, s42
	s_nop 0
	global_load_lds_dwordx4 v182, s[58:59]
	s_addc_u32 s31, s59, 0
	s_mov_b32 m0, s43
	s_nop 0
	global_load_lds_dwordx4 v180, s[30:31]
	s_nop 0
	s_mov_b32 m0, s44
	s_nop 0
	global_load_lds_dwordx4 v182, s[30:31]
	s_nop 0
	s_mov_b32 m0, s15
	s_nop 0
	global_load_lds_dwordx4 v0, s[60:61]
	s_nop 0
	s_mov_b32 m0, s45
	s_nop 0
	global_load_lds_dwordx4 v181, s[60:61]
	s_mul_i32 s4, s85, s87
	s_add_i32 s4, s4, s16
	s_cmp_lt_u32 s4, s46
	s_cselect_b64 s[8:9], -1, 0
	s_ashr_i32 s5, s4, 31
	s_lshr_b32 s5, s5, 29
	s_add_i32 s5, s4, s5
	s_ashr_i32 s90, s5, 3
	s_and_b32 s5, s5, -8
	s_sub_i32 s4, s4, s5
	s_lshr_b32 s5, s4, 31
	s_or_b32 s5, s78, s5
	s_mul_i32 s4, s5, s4
	s_add_i32 s4, s4, s90
	s_abs_i32 s90, s4
	v_readlane_b32 s91, v254, 48
	s_mul_hi_u32 s91, s90, s91
	s_mul_i32 s34, s91, s26
	s_sub_i32 s90, s90, s34
	s_ashr_i32 s5, s4, 31
	s_add_i32 s34, s91, 1
	s_sub_i32 s35, s90, s26
	s_cmp_ge_u32 s90, s26
	s_cselect_b32 s91, s34, s91
	s_cselect_b32 s90, s35, s90
	s_waitcnt vmcnt(8)
	s_waitcnt lgkmcnt(0)
	s_setprio 1
	s_barrier
; #define PG8_STAGE(bufoff, gbase, voff) do { _Pragma("unroll") for (int _i = 0; _i < 2; ++_i) { \
;         const unsigned _m0 = ldsb + (unsigned)((bufoff) + _i * 8192); const char* _gb = (const char*)(gbase); \
;         asm volatile("s_mov_b32 m0, %0\n\ts_nop 0\n\tglobal_load_lds_dwordx4 %1, %2" :: "s"(_m0), "v"((voff)[_i]), "s"(_gb) : "m0", "memory"); } } while (0)
; #define PG8_LDA(dst, b, h) do { _Pragma("unroll") for (int m = 0; m < 4; ++m) _Pragma("unroll") for (int k = 0; k < 2; ++k) dst[m][k] = *(const LAS bf16x8*)(lds + PG8_SA(b, h) + aoff + m * 2048 + k * 1024); } while (0)
; #define PG8_LDB(dst, b, h) do { _Pragma("unroll") for (int n = 0; n < 2; ++n) _Pragma("unroll") for (int k = 0; k < 2; ++k) dst[n][k] = *(const LAS bf16x8*)(lds + PG8_SB(b, h) + boff + n * 2048 + k * 1024); } while (0)
; #define PG8_MMA(ai, bj, At, Bt) do { __builtin_amdgcn_s_setprio(1); _Pragma("unroll") for (int m = 0; m < 4; ++m) _Pragma("unroll") for (int n = 0; n < 2; ++n) _Pragma("unroll") for (int k = 0; k < 2; ++k) \
;         acc[ai][bj][m][n] = __builtin_amdgcn_mfma_f32_16x16x32_bf16(Bt[n][k], At[m][k], acc[ai][bj][m][n], 0, 0, 0); __builtin_amdgcn_s_setprio(0); } while (0)
; #define PG8_WAIT_V(n) asm volatile("s_waitcnt vmcnt(" #n ")" ::: "memory")
; #define PG8_WAIT_L(n) asm volatile("s_waitcnt lgkmcnt(" #n ")" ::: "memory")
; #define PG8_BAR __builtin_amdgcn_s_barrier()
; #define PG8_SCHED __builtin_amdgcn_sched_barrier(0)
;     __device__ bool next(int i, Unit& u) const {
;     ...
;         int wgid = (int)L; { const int q = nwg / NXCD, r = nwg % NXCD, xcd = wgid % NXCD, off = wgid / NXCD; wgid = (xcd < r ? xcd * (q + 1) : r * (q + 1) + (xcd - r) * q) + off; }
;         const int nig = WGM * nN, gid = wgid / nig, fm = gid * WGM, gsz = (nM - fm) < WGM ? (nM - fm) : WGM;
;         u.pm = fm + ((wgid % nig) % gsz); u.pn = (wgid % nig) / gsz; return true;
; template <class Epi, bool ALIGN_EPI>
; __device__ __forceinline__ void gemm_phase(LAS unsigned char* lds, const Gemm g, const StaticOrder& S, const Epi& E) {
;     ...
;             PG8_WAIT_V(8); PG8_WAIT_L(0); PG8_BAR; PG8_MMA(1, 0, At, B0); PG8_MMA(1, 1, At, B1); PG8_BAR; PG8_SCHED;
;             PG8_LDB(B0, 1, 0); PG8_LDB(B1, 1, 1); PG8_SCHED; PG8_LDA(At, 1, 0); PG8_STAGE(PG8_SA(0, 1), a2 + hstepA, voffA);
;             PG8_WAIT_V(8); PG8_WAIT_L(0); PG8_BAR; PG8_MMA(0, 0, At, B0); PG8_MMA(0, 1, At, B1); PG8_BAR; PG8_SCHED;
	v_mfma_f32_16x16x32_bf16 v[62:65], v[74:77], v[162:165], 0
	v_mfma_f32_16x16x32_bf16 v[62:65], v[94:97], v[166:169], v[62:65]
	v_mfma_f32_16x16x32_bf16 v[58:61], v[114:117], v[162:165], 0
	v_mfma_f32_16x16x32_bf16 v[58:61], v[134:137], v[166:169], v[58:61]
	v_mfma_f32_16x16x32_bf16 v[54:57], v[146:149], v[162:165], 0
	v_mfma_f32_16x16x32_bf16 v[54:57], v[150:153], v[166:169], v[54:57]
	v_mfma_f32_16x16x32_bf16 v[50:53], v[154:157], v[162:165], 0
	v_mfma_f32_16x16x32_bf16 v[50:53], v[158:161], v[166:169], v[50:53]
	v_mfma_f32_16x16x32_bf16 v[34:37], v[154:157], v[170:173], 0
	v_mfma_f32_16x16x32_bf16 v[34:37], v[158:161], v[174:177], v[34:37]
	v_mfma_f32_16x16x32_bf16 v[38:41], v[146:149], v[170:173], 0
	v_mfma_f32_16x16x32_bf16 v[38:41], v[150:153], v[174:177], v[38:41]
	v_mfma_f32_16x16x32_bf16 v[42:45], v[114:117], v[170:173], 0
	v_mfma_f32_16x16x32_bf16 v[42:45], v[134:137], v[174:177], v[42:45]
	v_mfma_f32_16x16x32_bf16 v[46:49], v[74:77], v[170:173], 0
	v_mfma_f32_16x16x32_bf16 v[46:49], v[94:97], v[174:177], v[46:49]
	v_mfma_f32_16x16x32_bf16 v[30:33], v[74:77], v[188:191], 0
	v_mfma_f32_16x16x32_bf16 v[30:33], v[94:97], v[202:205], v[30:33]
	v_mfma_f32_16x16x32_bf16 v[26:29], v[114:117], v[188:191], 0
	v_mfma_f32_16x16x32_bf16 v[26:29], v[134:137], v[202:205], v[26:29]
	v_mfma_f32_16x16x32_bf16 v[22:25], v[146:149], v[188:191], 0
	v_mfma_f32_16x16x32_bf16 v[22:25], v[150:153], v[202:205], v[22:25]
	v_mfma_f32_16x16x32_bf16 v[18:21], v[154:157], v[188:191], 0
	v_mfma_f32_16x16x32_bf16 v[18:21], v[158:161], v[202:205], v[18:21]
	v_mfma_f32_16x16x32_bf16 v[2:5], v[154:157], v[206:209], 0
	v_mfma_f32_16x16x32_bf16 v[2:5], v[158:161], v[210:213], v[2:5]
	v_mfma_f32_16x16x32_bf16 v[6:9], v[146:149], v[206:209], 0
	v_mfma_f32_16x16x32_bf16 v[6:9], v[150:153], v[210:213], v[6:9]
	v_mfma_f32_16x16x32_bf16 v[10:13], v[114:117], v[206:209], 0
	v_mfma_f32_16x16x32_bf16 v[10:13], v[134:137], v[210:213], v[10:13]
	v_mfma_f32_16x16x32_bf16 v[14:17], v[74:77], v[206:209], 0
	v_mfma_f32_16x16x32_bf16 v[14:17], v[94:97], v[210:213], v[14:17]
	s_barrier
	s_setprio 0
	v_add_u32_e32 v134, 0x18000, v185
	v_add_u32_e32 v158, 0x1c000, v185
	ds_read_b128 v[74:77], v134
	ds_read_b128 v[94:97], v134 offset:1024
	ds_read_b128 v[114:117], v134 offset:2048
	ds_read_b128 v[134:137], v134 offset:3072
	ds_read_b128 v[146:149], v158
	ds_read_b128 v[150:153], v158 offset:1024
	ds_read_b128 v[154:157], v158 offset:2048
	ds_read_b128 v[158:161], v158 offset:3072
	ds_read_b128 v[162:165], v186 offset:32768
	ds_read_b128 v[166:169], v186 offset:33792
	ds_read_b128 v[170:173], v186 offset:34816
	ds_read_b128 v[174:177], v186 offset:35840
	ds_read_b128 v[188:191], v186 offset:36864
	ds_read_b128 v[202:205], v186 offset:37888
	ds_read_b128 v[206:209], v186 offset:38912
	ds_read_b128 v[210:213], v186 offset:39936
	s_add_u32 s30, s60, 0x40000
	s_addc_u32 s31, s61, 0
	s_mov_b32 m0, s55
	s_nop 0
	global_load_lds_dwordx4 v0, s[30:31]
	s_nop 0
	s_mov_b32 m0, s88
	s_nop 0
	global_load_lds_dwordx4 v181, s[30:31]
	s_add_i32 s34, s91, 1
	s_cmp_ge_u32 s90, s26
	s_cselect_b32 s90, s34, s91
	s_xor_b32 s90, s90, s5
	s_sub_i32 s5, s90, s5
	s_lshl_b32 s90, s5, 3
	s_sub_i32 s91, 0x80, s90
	s_min_i32 s91, s91, 8
	s_mul_i32 s5, s5, s26
	s_sub_i32 s4, s4, s5
	s_lshr_b32 s34, s4, 3
	s_and_b32 s4, s4, 7
	s_waitcnt vmcnt(8)
	s_waitcnt lgkmcnt(0)
	s_setprio 1
	s_barrier
	v_mfma_f32_16x16x32_bf16 v[142:145], v[74:77], v[162:165], v[142:145]
	v_mfma_f32_16x16x32_bf16 v[142:145], v[94:97], v[166:169], v[142:145]
	v_mfma_f32_16x16x32_bf16 v[138:141], v[114:117], v[162:165], v[138:141]
	v_mfma_f32_16x16x32_bf16 v[138:141], v[134:137], v[166:169], v[138:141]
	v_mfma_f32_16x16x32_bf16 v[130:133], v[146:149], v[162:165], v[130:133]
	v_mfma_f32_16x16x32_bf16 v[130:133], v[150:153], v[166:169], v[130:133]
	v_mfma_f32_16x16x32_bf16 v[126:129], v[154:157], v[162:165], v[126:129]
	v_mfma_f32_16x16x32_bf16 v[126:129], v[158:161], v[166:169], v[126:129]
	v_mfma_f32_16x16x32_bf16 v[106:109], v[154:157], v[170:173], v[106:109]
	v_mfma_f32_16x16x32_bf16 v[106:109], v[158:161], v[174:177], v[106:109]
	v_mfma_f32_16x16x32_bf16 v[110:113], v[146:149], v[170:173], v[110:113]
	v_mfma_f32_16x16x32_bf16 v[110:113], v[150:153], v[174:177], v[110:113]
	v_mfma_f32_16x16x32_bf16 v[118:121], v[114:117], v[170:173], v[118:121]
	v_mfma_f32_16x16x32_bf16 v[118:121], v[134:137], v[174:177], v[118:121]
	v_mfma_f32_16x16x32_bf16 v[122:125], v[74:77], v[170:173], v[122:125]
	v_mfma_f32_16x16x32_bf16 v[122:125], v[94:97], v[174:177], v[122:125]
	v_mfma_f32_16x16x32_bf16 v[102:105], v[74:77], v[188:191], v[102:105]
	v_mfma_f32_16x16x32_bf16 v[102:105], v[94:97], v[202:205], v[102:105]
	v_mfma_f32_16x16x32_bf16 v[98:101], v[114:117], v[188:191], v[98:101]
	v_mfma_f32_16x16x32_bf16 v[98:101], v[134:137], v[202:205], v[98:101]
	v_mfma_f32_16x16x32_bf16 v[90:93], v[146:149], v[188:191], v[90:93]
	v_mfma_f32_16x16x32_bf16 v[90:93], v[150:153], v[202:205], v[90:93]
	v_mfma_f32_16x16x32_bf16 v[86:89], v[154:157], v[188:191], v[86:89]
	v_mfma_f32_16x16x32_bf16 v[86:89], v[158:161], v[202:205], v[86:89]
	v_mfma_f32_16x16x32_bf16 v[66:69], v[154:157], v[206:209], v[66:69]
	v_mfma_f32_16x16x32_bf16 v[66:69], v[158:161], v[210:213], v[66:69]
	v_mfma_f32_16x16x32_bf16 v[70:73], v[146:149], v[206:209], v[70:73]
	v_mfma_f32_16x16x32_bf16 v[70:73], v[150:153], v[210:213], v[70:73]
	v_mfma_f32_16x16x32_bf16 v[78:81], v[114:117], v[206:209], v[78:81]
	v_mfma_f32_16x16x32_bf16 v[78:81], v[134:137], v[210:213], v[78:81]
	v_mfma_f32_16x16x32_bf16 v[82:85], v[74:77], v[206:209], v[82:85]
	v_mfma_f32_16x16x32_bf16 v[82:85], v[94:97], v[210:213], v[82:85]
	s_barrier
; #define PG8_STAGE(bufoff, gbase, voff) do { _Pragma("unroll") for (int _i = 0; _i < 2; ++_i) { \
;         const unsigned _m0 = ldsb + (unsigned)((bufoff) + _i * 8192); const char* _gb = (const char*)(gbase); \
;         asm volatile("s_mov_b32 m0, %0\n\ts_nop 0\n\tglobal_load_lds_dwordx4 %1, %2" :: "s"(_m0), "v"((voff)[_i]), "s"(_gb) : "m0", "memory"); } } while (0)
; #define PG8_LDA(dst, b, h) do { _Pragma("unroll") for (int m = 0; m < 4; ++m) _Pragma("unroll") for (int k = 0; k < 2; ++k) dst[m][k] = *(const LAS bf16x8*)(lds + PG8_SA(b, h) + aoff + m * 2048 + k * 1024); } while (0)
; #define PG8_MMA(ai, bj, At, Bt) do { __builtin_amdgcn_s_setprio(1); _Pragma("unroll") for (int m = 0; m < 4; ++m) _Pragma("unroll") for (int n = 0; n < 2; ++n) _Pragma("unroll") for (int k = 0; k < 2; ++k) \
;         acc[ai][bj][m][n] = __builtin_amdgcn_mfma_f32_16x16x32_bf16(Bt[n][k], At[m][k], acc[ai][bj][m][n], 0, 0, 0); __builtin_amdgcn_s_setprio(0); } while (0)
; #define PG8_WAIT_V(n) asm volatile("s_waitcnt vmcnt(" #n ")" ::: "memory")
; #define PG8_WAIT_L(n) asm volatile("s_waitcnt lgkmcnt(" #n ")" ::: "memory")
; #define PG8_BAR __builtin_amdgcn_s_barrier()
; #define PG8_SCHED __builtin_amdgcn_sched_barrier(0)
; template <class Epi, bool ALIGN_EPI>
; __device__ __forceinline__ void gemm_phase(LAS unsigned char* lds, const Gemm g, const StaticOrder& S, const Epi& E) {
;     ...
;         const char* nA = has_next ? (const char*)g.A + (size_t)nxt.pm * tstepA + (size_t)nxt.pn * g.a_pn_off * 2 + (size_t)(nxt.pm >> 4) * g.a_adj : cA; const char* nB = has_next ? (const char*)g.Bt + (size_t)nxt.pn * tstepB : cB;
;     ...
;             PG8_LDA(At, 1, 1); PG8_STAGE(PG8_SB(1, 0), b3, voffB); PG8_STAGE(PG8_SB(1, 1), b3 + hstepB, voffB); PG8_STAGE(PG8_SA(1, 0), a3, voffA);
;             PG8_WAIT_V(8); PG8_WAIT_L(0); PG8_BAR; PG8_MMA(1, 0, At, B0); PG8_MMA(1, 1, At, B1); PG8_BAR; PG8_SCHED;
;         }
	s_setprio 0
	ds_read_b128 v[162:165], v186 offset:49152
	ds_read_b128 v[166:169], v186 offset:50176
	ds_read_b128 v[170:173], v186 offset:51200
	ds_read_b128 v[174:177], v186 offset:52224
	ds_read_b128 v[188:191], v186 offset:53248
	ds_read_b128 v[202:205], v186 offset:54272
	ds_read_b128 v[206:209], v186 offset:55296
	ds_read_b128 v[210:213], v186 offset:56320
	s_add_u32 s30, s58, 0x80
	s_addc_u32 s31, s59, 0
	s_mov_b32 m0, s94
	s_nop 0
	global_load_lds_dwordx4 v180, s[30:31]
	s_nop 0
	s_mov_b32 m0, s95
	s_nop 0
	global_load_lds_dwordx4 v182, s[30:31]
	s_add_u32 s30, s58, 0x40080
	s_addc_u32 s31, s59, 0
	s_mov_b32 m0, s17
	s_nop 0
	global_load_lds_dwordx4 v180, s[30:31]
	s_nop 0
	s_mov_b32 m0, s53
	s_nop 0
	global_load_lds_dwordx4 v182, s[30:31]
	s_nop 0
	s_mov_b32 m0, s96
	s_nop 0
	global_load_lds_dwordx4 v0, s[56:57]
	s_nop 0
	s_mov_b32 m0, s97
	s_nop 0
	global_load_lds_dwordx4 v181, s[56:57]
	s_add_i32 s36, s4, s90
	s_ashr_i32 s37, s36, 31
	s_lshl_b64 s[4:5], s[36:37], 19
	s_add_u32 s38, s18, s4
	s_addc_u32 s39, s19, s5
	s_and_b64 s[4:5], s[8:9], exec
	s_cselect_b32 s4, s39, s59
	s_cselect_b32 s5, s38, s58
	s_ashr_i32 s35, s34, 31
	s_lshl_b64 vcc, s[34:35], 19
	s_add_u32 s90, s1, vcc_lo
	s_addc_u32 s91, s14, vcc_hi
	s_and_b64 vcc, s[8:9], exec
	s_cselect_b32 s35, s91, s57
	s_cselect_b32 s37, s90, s56
	s_waitcnt vmcnt(8)
	s_waitcnt lgkmcnt(0)
	s_setprio 1
	s_barrier
	v_mfma_f32_16x16x32_bf16 v[62:65], v[74:77], v[162:165], v[62:65]
	v_mfma_f32_16x16x32_bf16 v[62:65], v[94:97], v[166:169], v[62:65]
	v_mfma_f32_16x16x32_bf16 v[58:61], v[114:117], v[162:165], v[58:61]
	v_mfma_f32_16x16x32_bf16 v[58:61], v[134:137], v[166:169], v[58:61]
	v_mfma_f32_16x16x32_bf16 v[54:57], v[146:149], v[162:165], v[54:57]
	v_mfma_f32_16x16x32_bf16 v[54:57], v[150:153], v[166:169], v[54:57]
	v_mfma_f32_16x16x32_bf16 v[50:53], v[154:157], v[162:165], v[50:53]
	v_mfma_f32_16x16x32_bf16 v[50:53], v[158:161], v[166:169], v[50:53]
	v_mfma_f32_16x16x32_bf16 v[34:37], v[154:157], v[170:173], v[34:37]
	v_mfma_f32_16x16x32_bf16 v[34:37], v[158:161], v[174:177], v[34:37]
	v_mfma_f32_16x16x32_bf16 v[38:41], v[146:149], v[170:173], v[38:41]
	v_mfma_f32_16x16x32_bf16 v[38:41], v[150:153], v[174:177], v[38:41]
	v_mfma_f32_16x16x32_bf16 v[42:45], v[114:117], v[170:173], v[42:45]
	v_mfma_f32_16x16x32_bf16 v[42:45], v[134:137], v[174:177], v[42:45]
	v_mfma_f32_16x16x32_bf16 v[46:49], v[74:77], v[170:173], v[46:49]
	v_mfma_f32_16x16x32_bf16 v[46:49], v[94:97], v[174:177], v[46:49]
	v_mfma_f32_16x16x32_bf16 v[30:33], v[74:77], v[188:191], v[30:33]
	v_mfma_f32_16x16x32_bf16 v[30:33], v[94:97], v[202:205], v[30:33]
	v_mfma_f32_16x16x32_bf16 v[26:29], v[114:117], v[188:191], v[26:29]
	v_mfma_f32_16x16x32_bf16 v[26:29], v[134:137], v[202:205], v[26:29]
	v_mfma_f32_16x16x32_bf16 v[22:25], v[146:149], v[188:191], v[22:25]
	v_mfma_f32_16x16x32_bf16 v[22:25], v[150:153], v[202:205], v[22:25]
	v_mfma_f32_16x16x32_bf16 v[18:21], v[154:157], v[188:191], v[18:21]
	v_mfma_f32_16x16x32_bf16 v[18:21], v[158:161], v[202:205], v[18:21]
	v_mfma_f32_16x16x32_bf16 v[2:5], v[154:157], v[206:209], v[2:5]
	v_mfma_f32_16x16x32_bf16 v[2:5], v[158:161], v[210:213], v[2:5]
	v_mfma_f32_16x16x32_bf16 v[6:9], v[146:149], v[206:209], v[6:9]
	v_mfma_f32_16x16x32_bf16 v[6:9], v[150:153], v[210:213], v[6:9]
	v_mfma_f32_16x16x32_bf16 v[10:13], v[114:117], v[206:209], v[10:13]
	v_mfma_f32_16x16x32_bf16 v[10:13], v[134:137], v[210:213], v[10:13]
	v_mfma_f32_16x16x32_bf16 v[14:17], v[74:77], v[206:209], v[14:17]
	v_mfma_f32_16x16x32_bf16 v[14:17], v[94:97], v[210:213], v[14:17]
	s_barrier
	s_setprio 0
	s_add_i32 s50, s50, 2
	s_add_u32 s41, s41, 0x100
	s_addc_u32 s49, s49, 0
	s_add_u32 s92, s92, 0x100
	s_addc_u32 s93, s93, 0
	s_cmp_gt_u32 s50, 13
